# v38 plus nt hint on in-proj1 gate-section epilogue stores (gate is consumed only two phases later)
# baseline (speedup 1.0000x reference)
; DI unsigned pk2(float lo, float hi) { const f32x2_t v = {lo, hi}; const bf16x2_t b = __builtin_convertvector(v, bf16x2_t); return __builtin_bit_cast(unsigned, b); }
; DI float sigmoidf_(float z) { return __builtin_amdgcn_rcpf(1.f + __expf(-z)); }
;     DI void operator()(const f32x4 (&acc)[2][2][4][2], const Unit& u, int wr, int wc, int fr, int fq) const {
;     ...
;                     const int c = cc0 + bj * HALF;
;                     float v[8];
; #pragma unroll
;                     for (int j = 0; j < 4; ++j) { v[j] = acc[ai][bj][m][0][j]; v[4 + j] = acc[ai][bj][m][1][j]; }
;                     if (sec == 3) {
; #pragma unroll
;                         for (int j = 0; j < 8; ++j) v[j] = v[j] * sigmoidf_(v[j]);
;                         u32x4 w; w.x = pk2(v[0], v[1]); w.y = pk2(v[2], v[3]); w.z = pk2(v[4], v[5]); w.w = pk2(v[6], v[7]);
;                         *(u32x4*)(Gate + (size_t)r * D + c) = w;
.LBB0_105:
	v_ashrrev_i32_e32 v167, 31, v166
	v_lshlrev_b64 v[170:171], 11, v[166:167]
	s_andn2_b64 vcc, exec, s[8:9]
	v_lshl_add_u64 v[170:171], s[56:57], 0, v[170:171]
	v_lshlrev_b32_e32 v164, 1, v164
	s_cbranch_vccnz .LBB0_107
	v_mul_f32_e32 v154, 0xbfb8aa3b, v140
	v_exp_f32_e32 v154, v154
	v_mul_f32_e32 v165, 0xbfb8aa3b, v141
	v_exp_f32_e32 v165, v165
	v_mul_f32_e32 v167, 0xbfb8aa3b, v143
	v_add_f32_e32 v154, 1.0, v154
	v_rcp_f32_e32 v180, v154
	v_mul_f32_e32 v154, 0xbfb8aa3b, v142
	v_exp_f32_e32 v154, v154
	v_exp_f32_e32 v167, v167
	v_add_f32_e32 v165, 1.0, v165
	v_rcp_f32_e32 v181, v165
	v_add_f32_e32 v154, 1.0, v154
	v_mul_f32_e32 v165, 0xbfb8aa3b, v136
	v_rcp_f32_e32 v182, v154
	v_add_f32_e32 v154, 1.0, v167
	v_exp_f32_e32 v165, v165
	v_mul_f32_e32 v167, 0xbfb8aa3b, v137
	v_exp_f32_e32 v167, v167
	v_rcp_f32_e32 v183, v154
	v_add_f32_e32 v154, 1.0, v165
	v_mul_f32_e32 v165, 0xbfb8aa3b, v138
	v_rcp_f32_e32 v184, v154
	v_add_f32_e32 v154, 1.0, v167
	v_exp_f32_e32 v165, v165
	v_mul_f32_e32 v167, 0xbfb8aa3b, v139
	v_exp_f32_e32 v167, v167
	v_rcp_f32_e32 v185, v154
	v_add_f32_e32 v154, 1.0, v165
	v_rcp_f32_e32 v186, v154
	v_add_f32_e32 v154, 1.0, v167
	v_rcp_f32_e32 v187, v154
	v_pk_mul_f32 v[140:141], v[140:141], v[180:181]
	v_pk_mul_f32 v[142:143], v[142:143], v[182:183]
	v_pk_mul_f32 v[180:181], v[136:137], v[184:185]
	v_pk_mul_f32 v[182:183], v[138:139], v[186:187]
	v_mov_b32_e32 v165, v155
	v_cvt_pk_bf16_f32 v136, v140, v141
	v_cvt_pk_bf16_f32 v137, v142, v143
	v_cvt_pk_bf16_f32 v138, v180, v181
	v_cvt_pk_bf16_f32 v139, v182, v183
	v_lshl_add_u64 v[140:141], v[170:171], 0, v[164:165]
	global_store_dwordx4 v[140:141], v[136:139], off nt

; DI unsigned pk2(float lo, float hi) { const f32x2_t v = {lo, hi}; const bf16x2_t b = __builtin_convertvector(v, bf16x2_t); return __builtin_bit_cast(unsigned, b); }
; DI float sigmoidf_(float z) { return __builtin_amdgcn_rcpf(1.f + __expf(-z)); }
;     DI void operator()(const f32x4 (&acc)[2][2][4][2], const Unit& u, int wr, int wc, int fr, int fq) const {
;     ...
;                     if (sec == 3) {
; #pragma unroll
;                         for (int j = 0; j < 8; ++j) v[j] = v[j] * sigmoidf_(v[j]);
;                         u32x4 w; w.x = pk2(v[0], v[1]); w.y = pk2(v[2], v[3]); w.z = pk2(v[4], v[5]); w.w = pk2(v[6], v[7]);
;                         *(u32x4*)(Gate + (size_t)r * D + c) = w;
.LBB0_113:
	s_andn2_b64 vcc, exec, s[62:63]
	s_cbranch_vccnz .LBB0_115
	v_mul_f32_e32 v136, 0xbfb8aa3b, v132
	v_mul_f32_e32 v137, 0xbfb8aa3b, v133
	v_mul_f32_e32 v138, 0xbfb8aa3b, v134
	v_mul_f32_e32 v139, 0xbfb8aa3b, v135
	v_mul_f32_e32 v140, 0xbfb8aa3b, v128
	v_mul_f32_e32 v141, 0xbfb8aa3b, v129
	v_mul_f32_e32 v142, 0xbfb8aa3b, v130
	v_mul_f32_e32 v143, 0xbfb8aa3b, v131
	v_exp_f32_e32 v136, v136
	v_exp_f32_e32 v137, v137
	v_exp_f32_e32 v138, v138
	v_exp_f32_e32 v139, v139
	v_exp_f32_e32 v140, v140
	v_exp_f32_e32 v141, v141
	v_exp_f32_e32 v142, v142
	v_exp_f32_e32 v143, v143
	v_add_f32_e32 v136, 1.0, v136
	v_add_f32_e32 v137, 1.0, v137
	v_add_f32_e32 v138, 1.0, v138
	v_add_f32_e32 v139, 1.0, v139
	v_add_f32_e32 v140, 1.0, v140
	v_add_f32_e32 v141, 1.0, v141
	v_add_f32_e32 v142, 1.0, v142
	v_add_f32_e32 v143, 1.0, v143
	v_rcp_f32_e32 v136, v136
	v_rcp_f32_e32 v137, v137
	v_rcp_f32_e32 v138, v138
	v_rcp_f32_e32 v139, v139
	v_rcp_f32_e32 v140, v140
	v_rcp_f32_e32 v141, v141
	v_rcp_f32_e32 v142, v142
	v_rcp_f32_e32 v143, v143
	v_pk_mul_f32 v[132:133], v[132:133], v[136:137]
	v_pk_mul_f32 v[134:135], v[134:135], v[138:139]
	v_pk_mul_f32 v[136:137], v[128:129], v[140:141]
	v_pk_mul_f32 v[138:139], v[130:131], v[142:143]
	v_mov_b32_e32 v165, v155
	v_cvt_pk_bf16_f32 v128, v132, v133
	v_cvt_pk_bf16_f32 v129, v134, v135
	v_cvt_pk_bf16_f32 v130, v136, v137
	v_cvt_pk_bf16_f32 v131, v138, v139
	v_lshl_add_u64 v[132:133], v[170:171], 0, v[164:165]
	global_store_dwordx4 v[132:133], v[128:131], off offset:256 nt

; DI unsigned pk2(float lo, float hi) { const f32x2_t v = {lo, hi}; const bf16x2_t b = __builtin_convertvector(v, bf16x2_t); return __builtin_bit_cast(unsigned, b); }
; DI float sigmoidf_(float z) { return __builtin_amdgcn_rcpf(1.f + __expf(-z)); }
;     DI void operator()(const f32x4 (&acc)[2][2][4][2], const Unit& u, int wr, int wc, int fr, int fq) const {
;     ...
;                     if (sec == 3) {
; #pragma unroll
;                         for (int j = 0; j < 8; ++j) v[j] = v[j] * sigmoidf_(v[j]);
;                         u32x4 w; w.x = pk2(v[0], v[1]); w.y = pk2(v[2], v[3]); w.z = pk2(v[4], v[5]); w.w = pk2(v[6], v[7]);
;                         *(u32x4*)(Gate + (size_t)r * D + c) = w;
.LBB0_124:
	v_mul_f32_e32 v120, 0xbfb8aa3b, v116
	v_mul_f32_e32 v121, 0xbfb8aa3b, v117
	v_mul_f32_e32 v122, 0xbfb8aa3b, v118
	v_mul_f32_e32 v123, 0xbfb8aa3b, v119
	v_mul_f32_e32 v124, 0xbfb8aa3b, v112
	v_mul_f32_e32 v125, 0xbfb8aa3b, v113
	v_mul_f32_e32 v126, 0xbfb8aa3b, v114
	v_mul_f32_e32 v127, 0xbfb8aa3b, v115
	v_exp_f32_e32 v120, v120
	v_exp_f32_e32 v121, v121
	v_exp_f32_e32 v122, v122
	v_exp_f32_e32 v123, v123
	v_exp_f32_e32 v124, v124
	v_exp_f32_e32 v125, v125
	v_exp_f32_e32 v126, v126
	v_exp_f32_e32 v127, v127
	v_add_f32_e32 v120, 1.0, v120
	v_add_f32_e32 v121, 1.0, v121
	v_add_f32_e32 v122, 1.0, v122
	v_add_f32_e32 v123, 1.0, v123
	v_add_f32_e32 v124, 1.0, v124
	v_add_f32_e32 v125, 1.0, v125
	v_add_f32_e32 v126, 1.0, v126
	v_add_f32_e32 v127, 1.0, v127
	v_rcp_f32_e32 v120, v120
	v_rcp_f32_e32 v121, v121
	v_rcp_f32_e32 v122, v122
	v_rcp_f32_e32 v123, v123
	v_rcp_f32_e32 v124, v124
	v_rcp_f32_e32 v125, v125
	v_rcp_f32_e32 v126, v126
	v_rcp_f32_e32 v127, v127
	v_pk_mul_f32 v[116:117], v[116:117], v[120:121]
	v_pk_mul_f32 v[118:119], v[118:119], v[122:123]
	v_pk_mul_f32 v[120:121], v[112:113], v[124:125]
	v_pk_mul_f32 v[122:123], v[114:115], v[126:127]
	v_mov_b32_e32 v165, v155
	v_cvt_pk_bf16_f32 v112, v116, v117
	v_cvt_pk_bf16_f32 v113, v118, v119
	v_cvt_pk_bf16_f32 v114, v120, v121
	v_cvt_pk_bf16_f32 v115, v122, v123
	v_lshl_add_u64 v[116:117], v[130:131], 0, v[164:165]
	global_store_dwordx4 v[116:117], v[112:115], off offset:256 nt

; DI unsigned pk2(float lo, float hi) { const f32x2_t v = {lo, hi}; const bf16x2_t b = __builtin_convertvector(v, bf16x2_t); return __builtin_bit_cast(unsigned, b); }
; DI float sigmoidf_(float z) { return __builtin_amdgcn_rcpf(1.f + __expf(-z)); }
;     DI void operator()(const f32x4 (&acc)[2][2][4][2], const Unit& u, int wr, int wc, int fr, int fq) const {
;     ...
;                     if (sec == 3) {
; #pragma unroll
;                         for (int j = 0; j < 8; ++j) v[j] = v[j] * sigmoidf_(v[j]);
;                         u32x4 w; w.x = pk2(v[0], v[1]); w.y = pk2(v[2], v[3]); w.z = pk2(v[4], v[5]); w.w = pk2(v[6], v[7]);
;                         *(u32x4*)(Gate + (size_t)r * D + c) = w;
.LBB0_134:
	v_mul_f32_e32 v104, 0xbfb8aa3b, v100
	v_mul_f32_e32 v105, 0xbfb8aa3b, v101
	v_mul_f32_e32 v106, 0xbfb8aa3b, v102
	v_mul_f32_e32 v107, 0xbfb8aa3b, v103
	v_mul_f32_e32 v108, 0xbfb8aa3b, v96
	v_mul_f32_e32 v109, 0xbfb8aa3b, v97
	v_mul_f32_e32 v110, 0xbfb8aa3b, v98
	v_mul_f32_e32 v111, 0xbfb8aa3b, v99
	v_exp_f32_e32 v104, v104
	v_exp_f32_e32 v105, v105
	v_exp_f32_e32 v106, v106
	v_exp_f32_e32 v107, v107
	v_exp_f32_e32 v108, v108
	v_exp_f32_e32 v109, v109
	v_exp_f32_e32 v110, v110
	v_exp_f32_e32 v111, v111
	v_add_f32_e32 v104, 1.0, v104
	v_add_f32_e32 v105, 1.0, v105
	v_add_f32_e32 v106, 1.0, v106
	v_add_f32_e32 v107, 1.0, v107
	v_add_f32_e32 v108, 1.0, v108
	v_add_f32_e32 v109, 1.0, v109
	v_add_f32_e32 v110, 1.0, v110
	v_add_f32_e32 v111, 1.0, v111
	v_rcp_f32_e32 v104, v104
	v_rcp_f32_e32 v105, v105
	v_rcp_f32_e32 v106, v106
	v_rcp_f32_e32 v107, v107
	v_rcp_f32_e32 v108, v108
	v_rcp_f32_e32 v109, v109
	v_rcp_f32_e32 v110, v110
	v_rcp_f32_e32 v111, v111
	v_pk_mul_f32 v[100:101], v[100:101], v[104:105]
	v_pk_mul_f32 v[102:103], v[102:103], v[106:107]
	v_pk_mul_f32 v[104:105], v[96:97], v[108:109]
	v_pk_mul_f32 v[106:107], v[98:99], v[110:111]
	v_mov_b32_e32 v165, v155
	v_cvt_pk_bf16_f32 v96, v100, v101
	v_cvt_pk_bf16_f32 v97, v102, v103
	v_cvt_pk_bf16_f32 v98, v104, v105
	v_cvt_pk_bf16_f32 v99, v106, v107
	v_lshl_add_u64 v[100:101], v[114:115], 0, v[164:165]
	global_store_dwordx4 v[100:101], v[96:99], off offset:256 nt

; DI unsigned pk2(float lo, float hi) { const f32x2_t v = {lo, hi}; const bf16x2_t b = __builtin_convertvector(v, bf16x2_t); return __builtin_bit_cast(unsigned, b); }
; DI float sigmoidf_(float z) { return __builtin_amdgcn_rcpf(1.f + __expf(-z)); }
;     DI void operator()(const f32x4 (&acc)[2][2][4][2], const Unit& u, int wr, int wc, int fr, int fq) const {
;     ...
;                     if (sec == 3) {
; #pragma unroll
;                         for (int j = 0; j < 8; ++j) v[j] = v[j] * sigmoidf_(v[j]);
;                         u32x4 w; w.x = pk2(v[0], v[1]); w.y = pk2(v[2], v[3]); w.z = pk2(v[4], v[5]); w.w = pk2(v[6], v[7]);
;                         *(u32x4*)(Gate + (size_t)r * D + c) = w;
.LBB0_144:
	v_mul_f32_e32 v88, 0xbfb8aa3b, v84
	v_mul_f32_e32 v89, 0xbfb8aa3b, v85
	v_mul_f32_e32 v90, 0xbfb8aa3b, v86
	v_mul_f32_e32 v91, 0xbfb8aa3b, v87
	v_mul_f32_e32 v92, 0xbfb8aa3b, v80
	v_mul_f32_e32 v93, 0xbfb8aa3b, v81
	v_mul_f32_e32 v94, 0xbfb8aa3b, v82
	v_mul_f32_e32 v95, 0xbfb8aa3b, v83
	v_exp_f32_e32 v88, v88
	v_exp_f32_e32 v89, v89
	v_exp_f32_e32 v90, v90
	v_exp_f32_e32 v91, v91
	v_exp_f32_e32 v92, v92
	v_exp_f32_e32 v93, v93
	v_exp_f32_e32 v94, v94
	v_exp_f32_e32 v95, v95
	v_add_f32_e32 v88, 1.0, v88
	v_add_f32_e32 v89, 1.0, v89
	v_add_f32_e32 v90, 1.0, v90
	v_add_f32_e32 v91, 1.0, v91
	v_add_f32_e32 v92, 1.0, v92
	v_add_f32_e32 v93, 1.0, v93
	v_add_f32_e32 v94, 1.0, v94
	v_add_f32_e32 v95, 1.0, v95
	v_rcp_f32_e32 v88, v88
	v_rcp_f32_e32 v89, v89
	v_rcp_f32_e32 v90, v90
	v_rcp_f32_e32 v91, v91
	v_rcp_f32_e32 v92, v92
	v_rcp_f32_e32 v93, v93
	v_rcp_f32_e32 v94, v94
	v_rcp_f32_e32 v95, v95
	v_pk_mul_f32 v[84:85], v[84:85], v[88:89]
	v_pk_mul_f32 v[86:87], v[86:87], v[90:91]
	v_pk_mul_f32 v[88:89], v[80:81], v[92:93]
	v_pk_mul_f32 v[90:91], v[82:83], v[94:95]
	v_mov_b32_e32 v165, v155
	v_cvt_pk_bf16_f32 v80, v84, v85
	v_cvt_pk_bf16_f32 v81, v86, v87
	v_cvt_pk_bf16_f32 v82, v88, v89
	v_cvt_pk_bf16_f32 v83, v90, v91
	v_lshl_add_u64 v[84:85], v[98:99], 0, v[164:165]
	global_store_dwordx4 v[84:85], v[80:83], off offset:256 nt

; DI unsigned pk2(float lo, float hi) { const f32x2_t v = {lo, hi}; const bf16x2_t b = __builtin_convertvector(v, bf16x2_t); return __builtin_bit_cast(unsigned, b); }
; DI float sigmoidf_(float z) { return __builtin_amdgcn_rcpf(1.f + __expf(-z)); }
;     DI void operator()(const f32x4 (&acc)[2][2][4][2], const Unit& u, int wr, int wc, int fr, int fq) const {
;     ...
;                     if (sec == 3) {
; #pragma unroll
;                         for (int j = 0; j < 8; ++j) v[j] = v[j] * sigmoidf_(v[j]);
;                         u32x4 w; w.x = pk2(v[0], v[1]); w.y = pk2(v[2], v[3]); w.z = pk2(v[4], v[5]); w.w = pk2(v[6], v[7]);
;                         *(u32x4*)(Gate + (size_t)r * D + c) = w;
.LBB0_154:
	v_mul_f32_e32 v72, 0xbfb8aa3b, v68
	v_mul_f32_e32 v73, 0xbfb8aa3b, v69
	v_mul_f32_e32 v74, 0xbfb8aa3b, v70
	v_mul_f32_e32 v75, 0xbfb8aa3b, v71
	v_mul_f32_e32 v76, 0xbfb8aa3b, v64
	v_mul_f32_e32 v77, 0xbfb8aa3b, v65
	v_mul_f32_e32 v78, 0xbfb8aa3b, v66
	v_mul_f32_e32 v79, 0xbfb8aa3b, v67
	v_exp_f32_e32 v72, v72
	v_exp_f32_e32 v73, v73
	v_exp_f32_e32 v74, v74
	v_exp_f32_e32 v75, v75
	v_exp_f32_e32 v76, v76
	v_exp_f32_e32 v77, v77
	v_exp_f32_e32 v78, v78
	v_exp_f32_e32 v79, v79
	v_add_f32_e32 v72, 1.0, v72
	v_add_f32_e32 v73, 1.0, v73
	v_add_f32_e32 v74, 1.0, v74
	v_add_f32_e32 v75, 1.0, v75
	v_add_f32_e32 v76, 1.0, v76
	v_add_f32_e32 v77, 1.0, v77
	v_add_f32_e32 v78, 1.0, v78
	v_add_f32_e32 v79, 1.0, v79
	v_rcp_f32_e32 v72, v72
	v_rcp_f32_e32 v73, v73
	v_rcp_f32_e32 v74, v74
	v_rcp_f32_e32 v75, v75
	v_rcp_f32_e32 v76, v76
	v_rcp_f32_e32 v77, v77
	v_rcp_f32_e32 v78, v78
	v_rcp_f32_e32 v79, v79
	v_pk_mul_f32 v[68:69], v[68:69], v[72:73]
	v_pk_mul_f32 v[70:71], v[70:71], v[74:75]
	v_pk_mul_f32 v[72:73], v[64:65], v[76:77]
	v_pk_mul_f32 v[74:75], v[66:67], v[78:79]
	v_mov_b32_e32 v165, v155
	v_cvt_pk_bf16_f32 v64, v68, v69
	v_cvt_pk_bf16_f32 v65, v70, v71
	v_cvt_pk_bf16_f32 v66, v72, v73
	v_cvt_pk_bf16_f32 v67, v74, v75
	v_lshl_add_u64 v[68:69], v[82:83], 0, v[164:165]
	global_store_dwordx4 v[68:69], v[64:67], off offset:256 nt

; DI unsigned pk2(float lo, float hi) { const f32x2_t v = {lo, hi}; const bf16x2_t b = __builtin_convertvector(v, bf16x2_t); return __builtin_bit_cast(unsigned, b); }
; DI float sigmoidf_(float z) { return __builtin_amdgcn_rcpf(1.f + __expf(-z)); }
;     DI void operator()(const f32x4 (&acc)[2][2][4][2], const Unit& u, int wr, int wc, int fr, int fq) const {
;     ...
;                     if (sec == 3) {
; #pragma unroll
;                         for (int j = 0; j < 8; ++j) v[j] = v[j] * sigmoidf_(v[j]);
;                         u32x4 w; w.x = pk2(v[0], v[1]); w.y = pk2(v[2], v[3]); w.z = pk2(v[4], v[5]); w.w = pk2(v[6], v[7]);
;                         *(u32x4*)(Gate + (size_t)r * D + c) = w;
.LBB0_164:
	v_mul_f32_e32 v56, 0xbfb8aa3b, v44
	v_mul_f32_e32 v57, 0xbfb8aa3b, v45
	v_mul_f32_e32 v58, 0xbfb8aa3b, v46
	v_mul_f32_e32 v59, 0xbfb8aa3b, v47
	v_mul_f32_e32 v60, 0xbfb8aa3b, v40
	v_mul_f32_e32 v61, 0xbfb8aa3b, v41
	v_mul_f32_e32 v62, 0xbfb8aa3b, v42
	v_mul_f32_e32 v63, 0xbfb8aa3b, v43
	v_exp_f32_e32 v56, v56
	v_exp_f32_e32 v57, v57
	v_exp_f32_e32 v58, v58
	v_exp_f32_e32 v59, v59
	v_exp_f32_e32 v60, v60
	v_exp_f32_e32 v61, v61
	v_exp_f32_e32 v62, v62
	v_exp_f32_e32 v63, v63
	v_add_f32_e32 v56, 1.0, v56
	v_add_f32_e32 v57, 1.0, v57
	v_add_f32_e32 v58, 1.0, v58
	v_add_f32_e32 v59, 1.0, v59
	v_add_f32_e32 v60, 1.0, v60
	v_add_f32_e32 v61, 1.0, v61
	v_add_f32_e32 v62, 1.0, v62
	v_add_f32_e32 v63, 1.0, v63
	v_rcp_f32_e32 v56, v56
	v_rcp_f32_e32 v57, v57
	v_rcp_f32_e32 v58, v58
	v_rcp_f32_e32 v59, v59
	v_rcp_f32_e32 v60, v60
	v_rcp_f32_e32 v61, v61
	v_rcp_f32_e32 v62, v62
	v_rcp_f32_e32 v63, v63
	v_pk_mul_f32 v[44:45], v[44:45], v[56:57]
	v_pk_mul_f32 v[46:47], v[46:47], v[58:59]
	v_pk_mul_f32 v[56:57], v[40:41], v[60:61]
	v_pk_mul_f32 v[58:59], v[42:43], v[62:63]
	v_mov_b32_e32 v165, v155
	v_cvt_pk_bf16_f32 v40, v44, v45
	v_cvt_pk_bf16_f32 v41, v46, v47
	v_cvt_pk_bf16_f32 v42, v56, v57
	v_cvt_pk_bf16_f32 v43, v58, v59
	v_lshl_add_u64 v[44:45], v[66:67], 0, v[164:165]
	global_store_dwordx4 v[44:45], v[40:43], off offset:256 nt

; DI unsigned pk2(float lo, float hi) { const f32x2_t v = {lo, hi}; const bf16x2_t b = __builtin_convertvector(v, bf16x2_t); return __builtin_bit_cast(unsigned, b); }
; DI float sigmoidf_(float z) { return __builtin_amdgcn_rcpf(1.f + __expf(-z)); }
;     DI void operator()(const f32x4 (&acc)[2][2][4][2], const Unit& u, int wr, int wc, int fr, int fq) const {
;     ...
;                     if (sec == 3) {
; #pragma unroll
;                         for (int j = 0; j < 8; ++j) v[j] = v[j] * sigmoidf_(v[j]);
;                         u32x4 w; w.x = pk2(v[0], v[1]); w.y = pk2(v[2], v[3]); w.z = pk2(v[4], v[5]); w.w = pk2(v[6], v[7]);
;                         *(u32x4*)(Gate + (size_t)r * D + c) = w;
.LBB0_174:
	v_mul_f32_e32 v24, 0xbfb8aa3b, v20
	v_mul_f32_e32 v25, 0xbfb8aa3b, v21
	v_mul_f32_e32 v26, 0xbfb8aa3b, v22
	v_mul_f32_e32 v27, 0xbfb8aa3b, v23
	v_mul_f32_e32 v28, 0xbfb8aa3b, v16
	v_mul_f32_e32 v29, 0xbfb8aa3b, v17
	v_mul_f32_e32 v30, 0xbfb8aa3b, v18
	v_mul_f32_e32 v31, 0xbfb8aa3b, v19
	v_exp_f32_e32 v24, v24
	v_exp_f32_e32 v25, v25
	v_exp_f32_e32 v26, v26
	v_exp_f32_e32 v27, v27
	v_exp_f32_e32 v28, v28
	v_exp_f32_e32 v29, v29
	v_exp_f32_e32 v30, v30
	v_exp_f32_e32 v31, v31
	v_add_f32_e32 v24, 1.0, v24
	v_add_f32_e32 v25, 1.0, v25
	v_add_f32_e32 v26, 1.0, v26
	v_add_f32_e32 v27, 1.0, v27
	v_add_f32_e32 v28, 1.0, v28
	v_add_f32_e32 v29, 1.0, v29
	v_add_f32_e32 v30, 1.0, v30
	v_add_f32_e32 v31, 1.0, v31
	v_rcp_f32_e32 v24, v24
	v_rcp_f32_e32 v25, v25
	v_rcp_f32_e32 v26, v26
	v_rcp_f32_e32 v27, v27
	v_rcp_f32_e32 v28, v28
	v_rcp_f32_e32 v29, v29
	v_rcp_f32_e32 v30, v30
	v_rcp_f32_e32 v31, v31
	v_pk_mul_f32 v[20:21], v[20:21], v[24:25]
	v_pk_mul_f32 v[22:23], v[22:23], v[26:27]
	v_pk_mul_f32 v[24:25], v[16:17], v[28:29]
	v_pk_mul_f32 v[26:27], v[18:19], v[30:31]
	v_mov_b32_e32 v165, v155
	v_cvt_pk_bf16_f32 v16, v20, v21
	v_cvt_pk_bf16_f32 v17, v22, v23
	v_cvt_pk_bf16_f32 v18, v24, v25
	v_cvt_pk_bf16_f32 v19, v26, v27
	v_lshl_add_u64 v[20:21], v[42:43], 0, v[164:165]
	global_store_dwordx4 v[20:21], v[16:19], off offset:256 nt

; DI unsigned pk2(float lo, float hi) { const f32x2_t v = {lo, hi}; const bf16x2_t b = __builtin_convertvector(v, bf16x2_t); return __builtin_bit_cast(unsigned, b); }
; DI float sigmoidf_(float z) { return __builtin_amdgcn_rcpf(1.f + __expf(-z)); }
;     DI void operator()(const f32x4 (&acc)[2][2][4][2], const Unit& u, int wr, int wc, int fr, int fq) const {
;     ...
;                     if (sec == 3) {
; #pragma unroll
;                         for (int j = 0; j < 8; ++j) v[j] = v[j] * sigmoidf_(v[j]);
;                         u32x4 w; w.x = pk2(v[0], v[1]); w.y = pk2(v[2], v[3]); w.z = pk2(v[4], v[5]); w.w = pk2(v[6], v[7]);
;                         *(u32x4*)(Gate + (size_t)r * D + c) = w;
.LBB0_184:
	v_mul_f32_e32 v134, 0xbfb8aa3b, v124
	v_mul_f32_e32 v135, 0xbfb8aa3b, v125
	v_mul_f32_e32 v136, 0xbfb8aa3b, v126
	v_mul_f32_e32 v137, 0xbfb8aa3b, v127
	v_mul_f32_e32 v138, 0xbfb8aa3b, v120
	v_mul_f32_e32 v139, 0xbfb8aa3b, v121
	v_mul_f32_e32 v140, 0xbfb8aa3b, v122
	v_mul_f32_e32 v141, 0xbfb8aa3b, v123
	v_exp_f32_e32 v134, v134
	v_exp_f32_e32 v135, v135
	v_exp_f32_e32 v136, v136
	v_exp_f32_e32 v137, v137
	v_exp_f32_e32 v138, v138
	v_exp_f32_e32 v139, v139
	v_exp_f32_e32 v140, v140
	v_exp_f32_e32 v141, v141
	v_add_f32_e32 v134, 1.0, v134
	v_add_f32_e32 v135, 1.0, v135
	v_add_f32_e32 v136, 1.0, v136
	v_add_f32_e32 v137, 1.0, v137
	v_add_f32_e32 v138, 1.0, v138
	v_add_f32_e32 v139, 1.0, v139
	v_add_f32_e32 v140, 1.0, v140
	v_add_f32_e32 v141, 1.0, v141
	v_rcp_f32_e32 v134, v134
	v_rcp_f32_e32 v135, v135
	v_rcp_f32_e32 v136, v136
	v_rcp_f32_e32 v137, v137
	v_rcp_f32_e32 v138, v138
	v_rcp_f32_e32 v139, v139
	v_rcp_f32_e32 v140, v140
	v_rcp_f32_e32 v141, v141
	v_pk_mul_f32 v[124:125], v[124:125], v[134:135]
	v_pk_mul_f32 v[126:127], v[126:127], v[136:137]
	v_pk_mul_f32 v[134:135], v[120:121], v[138:139]
	v_pk_mul_f32 v[136:137], v[122:123], v[140:141]
	v_mov_b32_e32 v165, v155
	v_cvt_pk_bf16_f32 v120, v124, v125
	v_cvt_pk_bf16_f32 v121, v126, v127
	v_cvt_pk_bf16_f32 v122, v134, v135
	v_cvt_pk_bf16_f32 v123, v136, v137
	v_lshl_add_u64 v[124:125], v[130:131], 0, v[164:165]
	global_store_dwordx4 v[124:125], v[120:123], off nt
	s_and_b64 vcc, exec, s[8:9]
	s_mov_b64 s[60:61], -1
	s_cbranch_vccnz .LBB0_123

; DI unsigned pk2(float lo, float hi) { const f32x2_t v = {lo, hi}; const bf16x2_t b = __builtin_convertvector(v, bf16x2_t); return __builtin_bit_cast(unsigned, b); }
; DI float sigmoidf_(float z) { return __builtin_amdgcn_rcpf(1.f + __expf(-z)); }
;     DI void operator()(const f32x4 (&acc)[2][2][4][2], const Unit& u, int wr, int wc, int fr, int fq) const {
;     ...
;                     if (sec == 3) {
; #pragma unroll
;                         for (int j = 0; j < 8; ++j) v[j] = v[j] * sigmoidf_(v[j]);
;                         u32x4 w; w.x = pk2(v[0], v[1]); w.y = pk2(v[2], v[3]); w.z = pk2(v[4], v[5]); w.w = pk2(v[6], v[7]);
;                         *(u32x4*)(Gate + (size_t)r * D + c) = w;
.LBB0_190:
	v_mul_f32_e32 v118, 0xbfb8aa3b, v108
	v_mul_f32_e32 v119, 0xbfb8aa3b, v109
	v_mul_f32_e32 v120, 0xbfb8aa3b, v110
	v_mul_f32_e32 v121, 0xbfb8aa3b, v111
	v_mul_f32_e32 v122, 0xbfb8aa3b, v104
	v_mul_f32_e32 v123, 0xbfb8aa3b, v105
	v_mul_f32_e32 v124, 0xbfb8aa3b, v106
	v_mul_f32_e32 v125, 0xbfb8aa3b, v107
	v_exp_f32_e32 v118, v118
	v_exp_f32_e32 v119, v119
	v_exp_f32_e32 v120, v120
	v_exp_f32_e32 v121, v121
	v_exp_f32_e32 v122, v122
	v_exp_f32_e32 v123, v123
	v_exp_f32_e32 v124, v124
	v_exp_f32_e32 v125, v125
	v_add_f32_e32 v118, 1.0, v118
	v_add_f32_e32 v119, 1.0, v119
	v_add_f32_e32 v120, 1.0, v120
	v_add_f32_e32 v121, 1.0, v121
	v_add_f32_e32 v122, 1.0, v122
	v_add_f32_e32 v123, 1.0, v123
	v_add_f32_e32 v124, 1.0, v124
	v_add_f32_e32 v125, 1.0, v125
	v_rcp_f32_e32 v118, v118
	v_rcp_f32_e32 v119, v119
	v_rcp_f32_e32 v120, v120
	v_rcp_f32_e32 v121, v121
	v_rcp_f32_e32 v122, v122
	v_rcp_f32_e32 v123, v123
	v_rcp_f32_e32 v124, v124
	v_rcp_f32_e32 v125, v125
	v_pk_mul_f32 v[108:109], v[108:109], v[118:119]
	v_pk_mul_f32 v[110:111], v[110:111], v[120:121]
	v_pk_mul_f32 v[118:119], v[104:105], v[122:123]
	v_pk_mul_f32 v[120:121], v[106:107], v[124:125]
	v_mov_b32_e32 v165, v155
	v_cvt_pk_bf16_f32 v104, v108, v109
	v_cvt_pk_bf16_f32 v105, v110, v111
	v_cvt_pk_bf16_f32 v106, v118, v119
	v_cvt_pk_bf16_f32 v107, v120, v121
	v_lshl_add_u64 v[108:109], v[114:115], 0, v[164:165]
	global_store_dwordx4 v[108:109], v[104:107], off nt
	s_and_b64 vcc, exec, s[8:9]
	s_mov_b64 s[60:61], -1
	s_cbranch_vccnz .LBB0_133

; DI unsigned pk2(float lo, float hi) { const f32x2_t v = {lo, hi}; const bf16x2_t b = __builtin_convertvector(v, bf16x2_t); return __builtin_bit_cast(unsigned, b); }
; DI float sigmoidf_(float z) { return __builtin_amdgcn_rcpf(1.f + __expf(-z)); }
;     DI void operator()(const f32x4 (&acc)[2][2][4][2], const Unit& u, int wr, int wc, int fr, int fq) const {
;     ...
;                     if (sec == 3) {
; #pragma unroll
;                         for (int j = 0; j < 8; ++j) v[j] = v[j] * sigmoidf_(v[j]);
;                         u32x4 w; w.x = pk2(v[0], v[1]); w.y = pk2(v[2], v[3]); w.z = pk2(v[4], v[5]); w.w = pk2(v[6], v[7]);
;                         *(u32x4*)(Gate + (size_t)r * D + c) = w;
.LBB0_196:
	v_mul_f32_e32 v102, 0xbfb8aa3b, v92
	v_mul_f32_e32 v103, 0xbfb8aa3b, v93
	v_mul_f32_e32 v104, 0xbfb8aa3b, v94
	v_mul_f32_e32 v105, 0xbfb8aa3b, v95
	v_mul_f32_e32 v106, 0xbfb8aa3b, v88
	v_mul_f32_e32 v107, 0xbfb8aa3b, v89
	v_mul_f32_e32 v108, 0xbfb8aa3b, v90
	v_mul_f32_e32 v109, 0xbfb8aa3b, v91
	v_exp_f32_e32 v102, v102
	v_exp_f32_e32 v103, v103
	v_exp_f32_e32 v104, v104
	v_exp_f32_e32 v105, v105
	v_exp_f32_e32 v106, v106
	v_exp_f32_e32 v107, v107
	v_exp_f32_e32 v108, v108
	v_exp_f32_e32 v109, v109
	v_add_f32_e32 v102, 1.0, v102
	v_add_f32_e32 v103, 1.0, v103
	v_add_f32_e32 v104, 1.0, v104
	v_add_f32_e32 v105, 1.0, v105
	v_add_f32_e32 v106, 1.0, v106
	v_add_f32_e32 v107, 1.0, v107
	v_add_f32_e32 v108, 1.0, v108
	v_add_f32_e32 v109, 1.0, v109
	v_rcp_f32_e32 v102, v102
	v_rcp_f32_e32 v103, v103
	v_rcp_f32_e32 v104, v104
	v_rcp_f32_e32 v105, v105
	v_rcp_f32_e32 v106, v106
	v_rcp_f32_e32 v107, v107
	v_rcp_f32_e32 v108, v108
	v_rcp_f32_e32 v109, v109
	v_pk_mul_f32 v[92:93], v[92:93], v[102:103]
	v_pk_mul_f32 v[94:95], v[94:95], v[104:105]
	v_pk_mul_f32 v[102:103], v[88:89], v[106:107]
	v_pk_mul_f32 v[104:105], v[90:91], v[108:109]
	v_mov_b32_e32 v165, v155
	v_cvt_pk_bf16_f32 v88, v92, v93
	v_cvt_pk_bf16_f32 v89, v94, v95
	v_cvt_pk_bf16_f32 v90, v102, v103
	v_cvt_pk_bf16_f32 v91, v104, v105
	v_lshl_add_u64 v[92:93], v[98:99], 0, v[164:165]
	global_store_dwordx4 v[92:93], v[88:91], off nt
	s_and_b64 vcc, exec, s[8:9]
	s_mov_b64 s[60:61], -1
	s_cbranch_vccnz .LBB0_143

; DI unsigned pk2(float lo, float hi) { const f32x2_t v = {lo, hi}; const bf16x2_t b = __builtin_convertvector(v, bf16x2_t); return __builtin_bit_cast(unsigned, b); }
; DI float sigmoidf_(float z) { return __builtin_amdgcn_rcpf(1.f + __expf(-z)); }
;     DI void operator()(const f32x4 (&acc)[2][2][4][2], const Unit& u, int wr, int wc, int fr, int fq) const {
;     ...
;                     if (sec == 3) {
; #pragma unroll
;                         for (int j = 0; j < 8; ++j) v[j] = v[j] * sigmoidf_(v[j]);
;                         u32x4 w; w.x = pk2(v[0], v[1]); w.y = pk2(v[2], v[3]); w.z = pk2(v[4], v[5]); w.w = pk2(v[6], v[7]);
;                         *(u32x4*)(Gate + (size_t)r * D + c) = w;
.LBB0_202:
	v_mul_f32_e32 v87, 0xbfb8aa3b, v76
	v_exp_f32_e32 v87, v87
	v_mul_f32_e32 v88, 0xbfb8aa3b, v77
	v_exp_f32_e32 v88, v88
	v_mul_f32_e32 v90, 0xbfb8aa3b, v79
	v_add_f32_e32 v87, 1.0, v87
	v_exp_f32_e32 v91, v90
	v_add_f32_e32 v89, 1.0, v88
	v_rcp_f32_e32 v88, v87
	v_mul_f32_e32 v87, 0xbfb8aa3b, v78
	v_exp_f32_e32 v87, v87
	v_rcp_f32_e32 v89, v89
	v_mov_b32_e32 v165, v155
	v_add_f32_e32 v87, 1.0, v87
	v_rcp_f32_e32 v90, v87
	v_add_f32_e32 v87, 1.0, v91
	v_mul_f32_e32 v91, 0xbfb8aa3b, v72
	v_exp_f32_e32 v92, v91
	v_mul_f32_e32 v91, 0xbfb8aa3b, v73
	v_exp_f32_e32 v93, v91
	v_rcp_f32_e32 v91, v87
	v_add_f32_e32 v87, 1.0, v92
	v_rcp_f32_e32 v92, v87
	v_add_f32_e32 v87, 1.0, v93
	v_mul_f32_e32 v93, 0xbfb8aa3b, v74
	v_exp_f32_e32 v94, v93
	v_mul_f32_e32 v93, 0xbfb8aa3b, v75
	v_exp_f32_e32 v95, v93
	v_rcp_f32_e32 v93, v87
	v_add_f32_e32 v87, 1.0, v94
	v_rcp_f32_e32 v94, v87
	v_add_f32_e32 v87, 1.0, v95
	v_rcp_f32_e32 v95, v87
	v_pk_mul_f32 v[76:77], v[76:77], v[88:89]
	v_pk_mul_f32 v[78:79], v[78:79], v[90:91]
	v_pk_mul_f32 v[88:89], v[72:73], v[92:93]
	v_pk_mul_f32 v[90:91], v[74:75], v[94:95]
	v_cvt_pk_bf16_f32 v72, v76, v77
	v_cvt_pk_bf16_f32 v73, v78, v79
	v_cvt_pk_bf16_f32 v74, v88, v89
	v_cvt_pk_bf16_f32 v75, v90, v91
	v_lshl_add_u64 v[76:77], v[82:83], 0, v[164:165]
	global_store_dwordx4 v[76:77], v[72:75], off nt
	s_and_b64 vcc, exec, s[8:9]
	s_mov_b64 s[60:61], -1
	s_cbranch_vccnz .LBB0_153

; DI unsigned pk2(float lo, float hi) { const f32x2_t v = {lo, hi}; const bf16x2_t b = __builtin_convertvector(v, bf16x2_t); return __builtin_bit_cast(unsigned, b); }
; DI float sigmoidf_(float z) { return __builtin_amdgcn_rcpf(1.f + __expf(-z)); }
;     DI void operator()(const f32x4 (&acc)[2][2][4][2], const Unit& u, int wr, int wc, int fr, int fq) const {
;     ...
;                     if (sec == 3) {
; #pragma unroll
;                         for (int j = 0; j < 8; ++j) v[j] = v[j] * sigmoidf_(v[j]);
;                         u32x4 w; w.x = pk2(v[0], v[1]); w.y = pk2(v[2], v[3]); w.z = pk2(v[4], v[5]); w.w = pk2(v[6], v[7]);
;                         *(u32x4*)(Gate + (size_t)r * D + c) = w;
.LBB0_208:
	v_mul_f32_e32 v70, 0xbfb8aa3b, v60
	v_mul_f32_e32 v71, 0xbfb8aa3b, v61
	v_mul_f32_e32 v72, 0xbfb8aa3b, v62
	v_mul_f32_e32 v73, 0xbfb8aa3b, v63
	v_mul_f32_e32 v74, 0xbfb8aa3b, v56
	v_mul_f32_e32 v75, 0xbfb8aa3b, v57
	v_mul_f32_e32 v76, 0xbfb8aa3b, v58
	v_mul_f32_e32 v77, 0xbfb8aa3b, v59
	v_exp_f32_e32 v70, v70
	v_exp_f32_e32 v71, v71
	v_exp_f32_e32 v72, v72
	v_exp_f32_e32 v73, v73
	v_exp_f32_e32 v74, v74
	v_exp_f32_e32 v75, v75
	v_exp_f32_e32 v76, v76
	v_exp_f32_e32 v77, v77
	v_add_f32_e32 v70, 1.0, v70
	v_add_f32_e32 v71, 1.0, v71
	v_add_f32_e32 v72, 1.0, v72
	v_add_f32_e32 v73, 1.0, v73
	v_add_f32_e32 v74, 1.0, v74
	v_add_f32_e32 v75, 1.0, v75
	v_add_f32_e32 v76, 1.0, v76
	v_add_f32_e32 v77, 1.0, v77
	v_rcp_f32_e32 v70, v70
	v_rcp_f32_e32 v71, v71
	v_rcp_f32_e32 v72, v72
	v_rcp_f32_e32 v73, v73
	v_rcp_f32_e32 v74, v74
	v_rcp_f32_e32 v75, v75
	v_rcp_f32_e32 v76, v76
	v_rcp_f32_e32 v77, v77
	v_pk_mul_f32 v[60:61], v[60:61], v[70:71]
	v_pk_mul_f32 v[62:63], v[62:63], v[72:73]
	v_pk_mul_f32 v[70:71], v[56:57], v[74:75]
	v_pk_mul_f32 v[72:73], v[58:59], v[76:77]
	v_mov_b32_e32 v165, v155
	v_cvt_pk_bf16_f32 v56, v60, v61
	v_cvt_pk_bf16_f32 v57, v62, v63
	v_cvt_pk_bf16_f32 v58, v70, v71
	v_cvt_pk_bf16_f32 v59, v72, v73
	v_lshl_add_u64 v[60:61], v[66:67], 0, v[164:165]
	global_store_dwordx4 v[60:61], v[56:59], off nt
	s_and_b64 vcc, exec, s[8:9]
	s_mov_b64 s[60:61], -1
	s_cbranch_vccnz .LBB0_163

; DI unsigned pk2(float lo, float hi) { const f32x2_t v = {lo, hi}; const bf16x2_t b = __builtin_convertvector(v, bf16x2_t); return __builtin_bit_cast(unsigned, b); }
; DI float sigmoidf_(float z) { return __builtin_amdgcn_rcpf(1.f + __expf(-z)); }
;     DI void operator()(const f32x4 (&acc)[2][2][4][2], const Unit& u, int wr, int wc, int fr, int fq) const {
;     ...
;                     if (sec == 3) {
; #pragma unroll
;                         for (int j = 0; j < 8; ++j) v[j] = v[j] * sigmoidf_(v[j]);
;                         u32x4 w; w.x = pk2(v[0], v[1]); w.y = pk2(v[2], v[3]); w.z = pk2(v[4], v[5]); w.w = pk2(v[6], v[7]);
;                         *(u32x4*)(Gate + (size_t)r * D + c) = w;
.LBB0_214:
	v_mul_f32_e32 v46, 0xbfb8aa3b, v28
	v_mul_f32_e32 v47, 0xbfb8aa3b, v29
	v_mul_f32_e32 v56, 0xbfb8aa3b, v30
	v_mul_f32_e32 v57, 0xbfb8aa3b, v31
	v_mul_f32_e32 v58, 0xbfb8aa3b, v24
	v_mul_f32_e32 v59, 0xbfb8aa3b, v25
	v_mul_f32_e32 v60, 0xbfb8aa3b, v26
	v_mul_f32_e32 v61, 0xbfb8aa3b, v27
	v_exp_f32_e32 v46, v46
	v_exp_f32_e32 v47, v47
	v_exp_f32_e32 v56, v56
	v_exp_f32_e32 v57, v57
	v_exp_f32_e32 v58, v58
	v_exp_f32_e32 v59, v59
	v_exp_f32_e32 v60, v60
	v_exp_f32_e32 v61, v61
	v_add_f32_e32 v46, 1.0, v46
	v_add_f32_e32 v47, 1.0, v47
	v_add_f32_e32 v56, 1.0, v56
	v_add_f32_e32 v57, 1.0, v57
	v_add_f32_e32 v58, 1.0, v58
	v_add_f32_e32 v59, 1.0, v59
	v_add_f32_e32 v60, 1.0, v60
	v_add_f32_e32 v61, 1.0, v61
	v_rcp_f32_e32 v46, v46
	v_rcp_f32_e32 v47, v47
	v_rcp_f32_e32 v56, v56
	v_rcp_f32_e32 v57, v57
	v_rcp_f32_e32 v58, v58
	v_rcp_f32_e32 v59, v59
	v_rcp_f32_e32 v60, v60
	v_rcp_f32_e32 v61, v61
	v_pk_mul_f32 v[28:29], v[28:29], v[46:47]
	v_pk_mul_f32 v[30:31], v[30:31], v[56:57]
	v_pk_mul_f32 v[46:47], v[24:25], v[58:59]
	v_pk_mul_f32 v[56:57], v[26:27], v[60:61]
	v_mov_b32_e32 v165, v155
	v_cvt_pk_bf16_f32 v24, v28, v29
	v_cvt_pk_bf16_f32 v25, v30, v31
	v_cvt_pk_bf16_f32 v26, v46, v47
	v_cvt_pk_bf16_f32 v27, v56, v57
	v_lshl_add_u64 v[28:29], v[42:43], 0, v[164:165]
	global_store_dwordx4 v[28:29], v[24:27], off nt
	s_and_b64 vcc, exec, s[8:9]
	s_mov_b64 s[60:61], -1
	s_cbranch_vccnz .LBB0_173

; DI unsigned pk2(float lo, float hi) { const f32x2_t v = {lo, hi}; const bf16x2_t b = __builtin_convertvector(v, bf16x2_t); return __builtin_bit_cast(unsigned, b); }
; DI float sigmoidf_(float z) { return __builtin_amdgcn_rcpf(1.f + __expf(-z)); }
;     DI void operator()(const f32x4 (&acc)[2][2][4][2], const Unit& u, int wr, int wc, int fr, int fq) const {
;     ...
;                     if (sec == 3) {
; #pragma unroll
;                         for (int j = 0; j < 8; ++j) v[j] = v[j] * sigmoidf_(v[j]);
;                         u32x4 w; w.x = pk2(v[0], v[1]); w.y = pk2(v[2], v[3]); w.z = pk2(v[4], v[5]); w.w = pk2(v[6], v[7]);
;                         *(u32x4*)(Gate + (size_t)r * D + c) = w;
.LBB0_220:
	v_mul_f32_e32 v22, 0xbfb8aa3b, v12
	v_mul_f32_e32 v23, 0xbfb8aa3b, v13
	v_mul_f32_e32 v24, 0xbfb8aa3b, v14
	v_mul_f32_e32 v25, 0xbfb8aa3b, v15
	v_mul_f32_e32 v26, 0xbfb8aa3b, v8
	v_mul_f32_e32 v27, 0xbfb8aa3b, v9
	v_mul_f32_e32 v28, 0xbfb8aa3b, v10
	v_mul_f32_e32 v29, 0xbfb8aa3b, v11
	v_exp_f32_e32 v22, v22
	v_exp_f32_e32 v23, v23
	v_exp_f32_e32 v24, v24
	v_exp_f32_e32 v25, v25
	v_exp_f32_e32 v26, v26
	v_exp_f32_e32 v27, v27
	v_exp_f32_e32 v28, v28
	v_exp_f32_e32 v29, v29
	v_add_f32_e32 v22, 1.0, v22
	v_add_f32_e32 v23, 1.0, v23
	v_add_f32_e32 v24, 1.0, v24
	v_add_f32_e32 v25, 1.0, v25
	v_add_f32_e32 v26, 1.0, v26
	v_add_f32_e32 v27, 1.0, v27
	v_add_f32_e32 v28, 1.0, v28
	v_add_f32_e32 v29, 1.0, v29
	v_rcp_f32_e32 v22, v22
	v_rcp_f32_e32 v23, v23
	v_rcp_f32_e32 v24, v24
	v_rcp_f32_e32 v25, v25
	v_rcp_f32_e32 v26, v26
	v_rcp_f32_e32 v27, v27
	v_rcp_f32_e32 v28, v28
	v_rcp_f32_e32 v29, v29
	v_pk_mul_f32 v[12:13], v[12:13], v[22:23]
	v_pk_mul_f32 v[14:15], v[14:15], v[24:25]
	v_pk_mul_f32 v[22:23], v[8:9], v[26:27]
	v_pk_mul_f32 v[24:25], v[10:11], v[28:29]
	v_mov_b32_e32 v165, v155
	v_cvt_pk_bf16_f32 v8, v12, v13
	v_cvt_pk_bf16_f32 v9, v14, v15
	v_cvt_pk_bf16_f32 v10, v22, v23
	v_cvt_pk_bf16_f32 v11, v24, v25
	v_lshl_add_u64 v[12:13], v[18:19], 0, v[164:165]
	global_store_dwordx4 v[12:13], v[8:11], off nt
	s_and_b64 vcc, exec, s[8:9]
	s_mov_b64 s[8:9], -1
	s_cbranch_vccnz .LBB0_183

; DI unsigned pk2(float lo, float hi) { const f32x2_t v = {lo, hi}; const bf16x2_t b = __builtin_convertvector(v, bf16x2_t); return __builtin_bit_cast(unsigned, b); }
; DI float sigmoidf_(float z) { return __builtin_amdgcn_rcpf(1.f + __expf(-z)); }
;     DI void operator()(const f32x4 (&acc)[2][2][4][2], const Unit& u, int wr, int wc, int fr, int fq) const {
;     ...
;                     if (sec == 3) {
; #pragma unroll
;                         for (int j = 0; j < 8; ++j) v[j] = v[j] * sigmoidf_(v[j]);
;                         u32x4 w; w.x = pk2(v[0], v[1]); w.y = pk2(v[2], v[3]); w.z = pk2(v[4], v[5]); w.w = pk2(v[6], v[7]);
;                         *(u32x4*)(Gate + (size_t)r * D + c) = w;
.LBB0_226:
	s_nop 0
	v_mul_f32_e32 v8, 0xbfb8aa3b, v4
	v_mul_f32_e32 v9, 0xbfb8aa3b, v5
	v_mul_f32_e32 v10, 0xbfb8aa3b, v6
	v_mul_f32_e32 v11, 0xbfb8aa3b, v7
	v_mul_f32_e32 v12, 0xbfb8aa3b, v0
	v_mul_f32_e32 v13, 0xbfb8aa3b, v1
	v_mul_f32_e32 v14, 0xbfb8aa3b, v2
	v_mul_f32_e32 v15, 0xbfb8aa3b, v3
	v_exp_f32_e32 v8, v8
	v_exp_f32_e32 v9, v9
	v_exp_f32_e32 v10, v10
	v_exp_f32_e32 v11, v11
	v_exp_f32_e32 v12, v12
	v_exp_f32_e32 v13, v13
	v_exp_f32_e32 v14, v14
	v_exp_f32_e32 v15, v15
	v_add_f32_e32 v8, 1.0, v8
	v_add_f32_e32 v9, 1.0, v9
	v_add_f32_e32 v10, 1.0, v10
	v_add_f32_e32 v11, 1.0, v11
	v_add_f32_e32 v12, 1.0, v12
	v_add_f32_e32 v13, 1.0, v13
	v_add_f32_e32 v14, 1.0, v14
	v_add_f32_e32 v15, 1.0, v15
	v_rcp_f32_e32 v8, v8
	v_rcp_f32_e32 v9, v9
	v_rcp_f32_e32 v10, v10
	v_rcp_f32_e32 v11, v11
	v_rcp_f32_e32 v12, v12
	v_rcp_f32_e32 v13, v13
	v_rcp_f32_e32 v14, v14
	v_rcp_f32_e32 v15, v15
	v_pk_mul_f32 v[4:5], v[4:5], v[8:9]
	v_pk_mul_f32 v[6:7], v[6:7], v[10:11]
	v_pk_mul_f32 v[8:9], v[0:1], v[12:13]
	v_pk_mul_f32 v[10:11], v[2:3], v[14:15]
	v_mov_b32_e32 v165, v155
	v_cvt_pk_bf16_f32 v0, v4, v5
	v_cvt_pk_bf16_f32 v1, v6, v7
	v_cvt_pk_bf16_f32 v2, v8, v9
	v_cvt_pk_bf16_f32 v3, v10, v11
	v_lshl_add_u64 v[4:5], v[18:19], 0, v[164:165]
	global_store_dwordx4 v[4:5], v[0:3], off offset:256 nt
	s_branch .LBB0_88
